# norm1 (layer 0) and norm2 rewritten by hand: wave-owned rows, two rows in flight per wave; on top of table-conversion rewrite
# speedup vs baseline: 1.0087x; 1.0028x over previous
; DI int TID() { int t = threadIdx.x; asm volatile("" : "+v"(t)); return t; }
; DI u32 pack2(float a, float b) { return (u32)f2bf(a) | ((u32)f2bf(b) << 16); }
; DI void xcd_barrier(const XcdBarrier& b) {
;   asm volatile("s_waitcnt vmcnt(0)" ::: "memory");
;   __syncthreads();
;   if (threadIdx.x == 0) {
;     unsigned* bar = b.bar;
;     __builtin_amdgcn_s_waitcnt(0);
;     unsigned nloc = b.st[0], nx = b.st[1];
;     if (nloc == 0u) { xcd_barrier_complete(bar, b.x, nloc, nx); b.st[0] = nloc; b.st[1] = nx; }
; DI void phase_norm(const Params& p, int l, int which, int bid, int nblk) {
;   const int lane = TID() & 63, w = TID() >> 6;
;   const float* g = (which ? p.in[I_G2] : p.in[I_G1]) + l * 1024;
;   const bool from_input = (which == 0 && l == 0);
;   for (int row = bid * 4 + w; row < ROWS; row += nblk * 4) {
;     const int b = row / TPB, pos = row % TPB;
;     if (which == 1 && l == 1 && pos < CTXL) continue;
;     const float* xr = xrow_ptr(p, from_input, b, pos);
;     const float* mod = WSP(const float, OFF_MOD) + (size_t)(l * 17 + (pos < CTXL ? 16 : b)) * 6144 + which * 3072;
;     float x[16];
; #pragma unroll
;     for (int hh = 0; hh < 2; ++hh) {
;       const float4 a = *(const float4*)(xr + hh * 512 + lane * 8);
;       const float4 c = *(const float4*)(xr + hh * 512 + lane * 8 + 4);
;       x[hh * 8 + 0] = a.x; x[hh * 8 + 1] = a.y; x[hh * 8 + 2] = a.z; x[hh * 8 + 3] = a.w;
;       x[hh * 8 + 4] = c.x; x[hh * 8 + 5] = c.y; x[hh * 8 + 6] = c.z; x[hh * 8 + 7] = c.w;
;     }
;     float ss = 0.f;
; #pragma unroll
;     for (int i = 0; i < 16; ++i) ss += x[i] * x[i];
;     ss = wave_sum(ss);
;     const float rs = rsqrtf(ss * (1.f / 1024.f) + EPSF);
; #pragma unroll
;     for (int hh = 0; hh < 2; ++hh) {
;       const int c0 = hh * 512 + lane * 8;
;       float y[8];
; #pragma unroll
;       for (int i = 0; i < 8; ++i) {
;         const float yn = x[hh * 8 + i] * rs * g[c0 + i];
;         y[i] = yn * (1.f + mod[1024 + c0 + i]) + mod[c0 + i];
;       }
;       uint4 o = {pack2(y[0], y[1]), pack2(y[2], y[3]), pack2(y[4], y[5]), pack2(y[6], y[7])};
;       *(uint4*)&WSP(u16, OFF_ACT)[(size_t)row * 1024 + c0] = o;
;     }
;   }
; }
.LBB0_355:
	s_mul_i32 s11, s24, 17
	s_mov_b64 s[0:1], exec
	s_cmp_lg_u64 s[70:71], 0
	s_cbranch_scc1 .Ln1_done
	v_readlane_b32 s66, v253, 3
	v_readlane_b32 s67, v253, 4
	v_readlane_b32 s78, v253, 7
	v_readlane_b32 s79, v253, 8
	v_lshrrev_b32_e32 v4, 6, v218
	v_readlane_b32 s19, v255, 58
	v_and_b32_e32 v10, 63, v218
	v_readlane_b32 s48, v253, 15
	v_readlane_b32 s49, v253, 16
	v_readfirstlane_b32 s22, v4
	s_add_i32 s19, s19, s22
	s_mov_b32 s23, 99
	s_mov_b32 s25, 99
	s_movk_i32 s26, 18
	s_cmp_eq_u64 s[70:71], 0
	s_cbranch_scc1 .Ln1_noskip
	s_lshr_b32 s23, s19, 8
	s_add_i32 s25, s23, 9
	s_movk_i32 s26, 16
.Ln1_noskip:
	s_mul_i32 s65, s24, 17
	s_lshl_b32 s16, s24, 12
	s_add_u32 s48, s48, s16
	s_addc_u32 s49, s49, 0
	v_lshlrev_b32_e32 v4, 4, v10
	v_lshlrev_b32_e32 v9, 3, v10
	global_load_dwordx4 v[16:19], v4, s[48:49]
	global_load_dwordx4 v[20:23], v4, s[48:49] offset:1024
	global_load_dwordx4 v[24:27], v4, s[48:49] offset:2048
	global_load_dwordx4 v[28:31], v4, s[48:49] offset:3072
	v_xor_b32_e32 v5, 16, v10
	v_xor_b32_e32 v6, 32, v10
	v_lshlrev_b32_e32 v5, 2, v5
	v_lshlrev_b32_e32 v6, 2, v6
	s_mov_b32 s27, 0
	s_cmp_ge_u32 s27, s23
	s_addc_u32 s44, s27, 0
	s_cmp_ge_u32 s44, s25
	s_addc_u32 s44, s44, 0
	s_lshl_b32 s44, s44, 11
	s_add_i32 s44, s44, s19
	s_mul_hi_u32 s46, s44, 0x38e38e39
	s_lshr_b32 s46, s46, 9
	s_mul_i32 s16, s46, 0x900
	s_sub_u32 s16, s44, s16
	s_cmp_lt_u32 s16, 0x100
	s_cbranch_scc1 .Ln1_1_ctx
	s_lshl_b32 s17, s46, 11
	s_add_i32 s17, s17, s16
	s_add_i32 s17, s17, 0xffffff00
	s_lshl_b32 s17, s17, 12
	s_add_u32 s30, s66, s17
	s_addc_u32 s31, s67, 0
	s_add_i32 s46, s46, s65
	s_branch .Ln1_1_ptr
.Ln1_1_ctx:
	s_lshl_b32 s17, s46, 8
	s_add_i32 s17, s17, s16
	s_lshl_b32 s17, s17, 12
	s_add_u32 s30, s78, s17
	s_addc_u32 s31, s79, 0
	s_add_i32 s46, s65, 16
.Ln1_1_ptr:
	s_mul_i32 s46, s46, 0x6000
	s_add_u32 s36, s96, 0x1be04000
	s_addc_u32 s37, s97, 0
	s_add_u32 s36, s36, s46
	s_addc_u32 s37, s37, 0
	s_add_u32 s38, s36, 0x1000
	s_addc_u32 s39, s37, 0
	s_lshl_b32 s17, s44, 11
	s_add_u32 s50, s6, s17
	s_addc_u32 s51, s7, 0
	global_load_dwordx4 v[32:35], v4, s[30:31]
	global_load_dwordx4 v[36:39], v4, s[30:31] offset:1024
	global_load_dwordx4 v[40:43], v4, s[30:31] offset:2048
	global_load_dwordx4 v[44:47], v4, s[30:31] offset:3072
	global_load_dwordx4 v[64:67], v4, s[36:37]
	global_load_dwordx4 v[68:71], v4, s[36:37] offset:1024
	global_load_dwordx4 v[72:75], v4, s[36:37] offset:2048
	global_load_dwordx4 v[76:79], v4, s[36:37] offset:3072
	global_load_dwordx4 v[80:83], v4, s[38:39]
	global_load_dwordx4 v[84:87], v4, s[38:39] offset:1024
	global_load_dwordx4 v[88:91], v4, s[38:39] offset:2048
	global_load_dwordx4 v[92:95], v4, s[38:39] offset:3072
.Ln1_top:
	s_add_i32 s28, s27, 1
	s_cmp_ge_u32 s28, s23
	s_addc_u32 s44, s28, 0
	s_cmp_ge_u32 s44, s25
	s_addc_u32 s44, s44, 0
	s_lshl_b32 s44, s44, 11
	s_add_i32 s44, s44, s19
	s_mul_hi_u32 s46, s44, 0x38e38e39
	s_lshr_b32 s46, s46, 9
	s_mul_i32 s16, s46, 0x900
	s_sub_u32 s16, s44, s16
	s_cmp_lt_u32 s16, 0x100
	s_cbranch_scc1 .Ln1_2_ctx
	s_lshl_b32 s17, s46, 11
	s_add_i32 s17, s17, s16
	s_add_i32 s17, s17, 0xffffff00
	s_lshl_b32 s17, s17, 12
	s_add_u32 s30, s66, s17
	s_addc_u32 s31, s67, 0
	s_add_i32 s46, s46, s65
	s_branch .Ln1_2_ptr

; DI u32 pack2(float a, float b) { return (u32)f2bf(a) | ((u32)f2bf(b) << 16); }
; DI void phase_norm(const Params& p, int l, int which, int bid, int nblk) {
;     ...
;     float x[16];
; #pragma unroll
;     for (int hh = 0; hh < 2; ++hh) {
;       const float4 a = *(const float4*)(xr + hh * 512 + lane * 8);
;       const float4 c = *(const float4*)(xr + hh * 512 + lane * 8 + 4);
;       x[hh * 8 + 0] = a.x; x[hh * 8 + 1] = a.y; x[hh * 8 + 2] = a.z; x[hh * 8 + 3] = a.w;
;       x[hh * 8 + 4] = c.x; x[hh * 8 + 5] = c.y; x[hh * 8 + 6] = c.z; x[hh * 8 + 7] = c.w;
;     }
;     float ss = 0.f;
; #pragma unroll
;     for (int i = 0; i < 16; ++i) ss += x[i] * x[i];
;     ss = wave_sum(ss);
;     const float rs = rsqrtf(ss * (1.f / 1024.f) + EPSF);
; #pragma unroll
;     for (int hh = 0; hh < 2; ++hh) {
;       const int c0 = hh * 512 + lane * 8;
;       float y[8];
; #pragma unroll
;       for (int i = 0; i < 8; ++i) {
;         const float yn = x[hh * 8 + i] * rs * g[c0 + i];
;         y[i] = yn * (1.f + mod[1024 + c0 + i]) + mod[c0 + i];
;       }
;       uint4 o = {pack2(y[0], y[1]), pack2(y[2], y[3]), pack2(y[4], y[5]), pack2(y[6], y[7])};
;       *(uint4*)&WSP(u16, OFF_ACT)[(size_t)row * 1024 + c0] = o;
;     }
.Ln1_2_ptr:
	s_mul_i32 s46, s46, 0x6000
	s_add_u32 s36, s96, 0x1be04000
	s_addc_u32 s37, s97, 0
	s_add_u32 s36, s36, s46
	s_addc_u32 s37, s37, 0
	s_add_u32 s38, s36, 0x1000
	s_addc_u32 s39, s37, 0
	s_lshl_b32 s17, s44, 11
	s_add_u32 s56, s6, s17
	s_addc_u32 s57, s7, 0
	global_load_dwordx4 v[48:51], v4, s[30:31]
	global_load_dwordx4 v[52:55], v4, s[30:31] offset:1024
	global_load_dwordx4 v[56:59], v4, s[30:31] offset:2048
	global_load_dwordx4 v[60:63], v4, s[30:31] offset:3072
	global_load_dwordx4 v[96:99], v4, s[36:37]
	global_load_dwordx4 v[100:103], v4, s[36:37] offset:1024
	global_load_dwordx4 v[104:107], v4, s[36:37] offset:2048
	global_load_dwordx4 v[108:111], v4, s[36:37] offset:3072
	global_load_dwordx4 v[112:115], v4, s[38:39]
	global_load_dwordx4 v[116:119], v4, s[38:39] offset:1024
	global_load_dwordx4 v[120:123], v4, s[38:39] offset:2048
	global_load_dwordx4 v[124:127], v4, s[38:39] offset:3072
	s_waitcnt vmcnt(12)
	v_mul_f32_e32 v7, v32, v32
	v_fmac_f32_e32 v7, v33, v33
	v_fmac_f32_e32 v7, v34, v34
	v_fmac_f32_e32 v7, v35, v35
	v_fmac_f32_e32 v7, v36, v36
	v_fmac_f32_e32 v7, v37, v37
	v_fmac_f32_e32 v7, v38, v38
	v_fmac_f32_e32 v7, v39, v39
	v_fmac_f32_e32 v7, v40, v40
	v_fmac_f32_e32 v7, v41, v41
	v_fmac_f32_e32 v7, v42, v42
	v_fmac_f32_e32 v7, v43, v43
	v_fmac_f32_e32 v7, v44, v44
	v_fmac_f32_e32 v7, v45, v45
	v_fmac_f32_e32 v7, v46, v46
	v_fmac_f32_e32 v7, v47, v47
	s_nop 1
	v_add_f32_dpp v7, v7, v7 quad_perm:[1,0,3,2] row_mask:0xf bank_mask:0xf
	s_nop 1
	v_add_f32_dpp v7, v7, v7 quad_perm:[2,3,0,1] row_mask:0xf bank_mask:0xf
	s_nop 1
	v_add_f32_dpp v7, v7, v7 row_half_mirror row_mask:0xf bank_mask:0xf
	s_nop 1
	v_add_f32_dpp v7, v7, v7 row_mirror row_mask:0xf bank_mask:0xf
	s_nop 1
	ds_bpermute_b32 v8, v5, v7
	s_waitcnt lgkmcnt(0)
	v_add_f32_e32 v7, v7, v8
	ds_bpermute_b32 v8, v6, v7
	s_waitcnt lgkmcnt(0)
	v_add_f32_e32 v7, v7, v8
	v_mov_b32_e32 v8, 0x358637bd
	v_fmac_f32_e32 v8, 0x3a800000, v7
	v_rsq_f32_e32 v8, v8
	s_nop 0
	v_mul_f32_e32 v32, v32, v8
	v_mul_f32_e32 v33, v33, v8
	v_mul_f32_e32 v34, v34, v8
	v_mul_f32_e32 v35, v35, v8
	v_mul_f32_e32 v36, v36, v8
	v_mul_f32_e32 v37, v37, v8
	v_mul_f32_e32 v38, v38, v8
	v_mul_f32_e32 v39, v39, v8
	v_mul_f32_e32 v40, v40, v8
	v_mul_f32_e32 v41, v41, v8
	v_mul_f32_e32 v42, v42, v8
	v_mul_f32_e32 v43, v43, v8
	v_mul_f32_e32 v44, v44, v8
	v_mul_f32_e32 v45, v45, v8
	v_mul_f32_e32 v46, v46, v8
	v_mul_f32_e32 v47, v47, v8
	v_mul_f32_e32 v32, v32, v16
	v_mul_f32_e32 v33, v33, v17
	v_mul_f32_e32 v34, v34, v18
	v_mul_f32_e32 v35, v35, v19
	v_mul_f32_e32 v36, v36, v20
	v_mul_f32_e32 v37, v37, v21
	v_mul_f32_e32 v38, v38, v22
	v_mul_f32_e32 v39, v39, v23
	v_mul_f32_e32 v40, v40, v24
	v_mul_f32_e32 v41, v41, v25
	v_mul_f32_e32 v42, v42, v26
	v_mul_f32_e32 v43, v43, v27
	v_mul_f32_e32 v44, v44, v28
	v_mul_f32_e32 v45, v45, v29
	v_mul_f32_e32 v46, v46, v30
	v_mul_f32_e32 v47, v47, v31
	v_add_f32_e32 v80, 1.0, v80
	v_add_f32_e32 v81, 1.0, v81
	v_add_f32_e32 v82, 1.0, v82
	v_add_f32_e32 v83, 1.0, v83
	v_add_f32_e32 v84, 1.0, v84
	v_add_f32_e32 v85, 1.0, v85
	v_add_f32_e32 v86, 1.0, v86
	v_add_f32_e32 v87, 1.0, v87
	v_add_f32_e32 v88, 1.0, v88
	v_add_f32_e32 v89, 1.0, v89
	v_add_f32_e32 v90, 1.0, v90
	v_add_f32_e32 v91, 1.0, v91
	v_add_f32_e32 v92, 1.0, v92
	v_add_f32_e32 v93, 1.0, v93
	v_add_f32_e32 v94, 1.0, v94
	v_add_f32_e32 v95, 1.0, v95
	v_fma_f32 v32, v32, v80, v64
	v_fma_f32 v33, v33, v81, v65
	v_fma_f32 v34, v34, v82, v66
	v_fma_f32 v35, v35, v83, v67
	v_fma_f32 v36, v36, v84, v68
	v_fma_f32 v37, v37, v85, v69
	v_fma_f32 v38, v38, v86, v70
	v_fma_f32 v39, v39, v87, v71
	v_fma_f32 v40, v40, v88, v72
	v_fma_f32 v41, v41, v89, v73
	v_fma_f32 v42, v42, v90, v74
	v_fma_f32 v43, v43, v91, v75
	v_fma_f32 v44, v44, v92, v76
	v_fma_f32 v45, v45, v93, v77
	v_fma_f32 v46, v46, v94, v78
	v_fma_f32 v47, v47, v95, v79
	v_cvt_pk_bf16_f32 v32, v32, v33
	v_cvt_pk_bf16_f32 v33, v34, v35
	v_cvt_pk_bf16_f32 v34, v36, v37
	v_cvt_pk_bf16_f32 v35, v38, v39
	v_cvt_pk_bf16_f32 v36, v40, v41
	v_cvt_pk_bf16_f32 v37, v42, v43
	v_cvt_pk_bf16_f32 v38, v44, v45
	v_cvt_pk_bf16_f32 v39, v46, v47
	s_nop 0
	global_store_dwordx2 v9, v[32:33], s[50:51]
	global_store_dwordx2 v9, v[34:35], s[50:51] offset:512
	global_store_dwordx2 v9, v[36:37], s[50:51] offset:1024
	global_store_dwordx2 v9, v[38:39], s[50:51] offset:1536
	s_add_i32 s27, s27, 2
	s_cmp_lt_u32 s27, s26
	s_cselect_b32 s28, s27, 0
	s_cmp_ge_u32 s28, s23
	s_addc_u32 s44, s28, 0
	s_cmp_ge_u32 s44, s25
	s_addc_u32 s44, s44, 0
	s_lshl_b32 s44, s44, 11
	s_add_i32 s44, s44, s19
	s_mul_hi_u32 s46, s44, 0x38e38e39
	s_lshr_b32 s46, s46, 9
	s_mul_i32 s16, s46, 0x900
	s_sub_u32 s16, s44, s16
	s_cmp_lt_u32 s16, 0x100
	s_cbranch_scc1 .Ln1_3_ctx
	s_lshl_b32 s17, s46, 11
	s_add_i32 s17, s17, s16
	s_add_i32 s17, s17, 0xffffff00
	s_lshl_b32 s17, s17, 12
	s_add_u32 s30, s66, s17
	s_addc_u32 s31, s67, 0
	s_add_i32 s46, s46, s65
	s_branch .Ln1_3_ptr

; DI u32 pack2(float a, float b) { return (u32)f2bf(a) | ((u32)f2bf(b) << 16); }
; DI void phase_norm(const Params& p, int l, int which, int bid, int nblk) {
;     ...
;     float x[16];
; #pragma unroll
;     for (int hh = 0; hh < 2; ++hh) {
;       const float4 a = *(const float4*)(xr + hh * 512 + lane * 8);
;       const float4 c = *(const float4*)(xr + hh * 512 + lane * 8 + 4);
;       x[hh * 8 + 0] = a.x; x[hh * 8 + 1] = a.y; x[hh * 8 + 2] = a.z; x[hh * 8 + 3] = a.w;
;       x[hh * 8 + 4] = c.x; x[hh * 8 + 5] = c.y; x[hh * 8 + 6] = c.z; x[hh * 8 + 7] = c.w;
;     }
;     float ss = 0.f;
; #pragma unroll
;     for (int i = 0; i < 16; ++i) ss += x[i] * x[i];
;     ss = wave_sum(ss);
;     const float rs = rsqrtf(ss * (1.f / 1024.f) + EPSF);
; #pragma unroll
;     for (int hh = 0; hh < 2; ++hh) {
;       const int c0 = hh * 512 + lane * 8;
;       float y[8];
; #pragma unroll
;       for (int i = 0; i < 8; ++i) {
;         const float yn = x[hh * 8 + i] * rs * g[c0 + i];
;         y[i] = yn * (1.f + mod[1024 + c0 + i]) + mod[c0 + i];
;       }
;       uint4 o = {pack2(y[0], y[1]), pack2(y[2], y[3]), pack2(y[4], y[5]), pack2(y[6], y[7])};
;       *(uint4*)&WSP(u16, OFF_ACT)[(size_t)row * 1024 + c0] = o;
;     }
.Ln1_3_ptr:
	s_mul_i32 s46, s46, 0x6000
	s_add_u32 s36, s96, 0x1be04000
	s_addc_u32 s37, s97, 0
	s_add_u32 s36, s36, s46
	s_addc_u32 s37, s37, 0
	s_add_u32 s38, s36, 0x1000
	s_addc_u32 s39, s37, 0
	s_lshl_b32 s17, s44, 11
	s_add_u32 s50, s6, s17
	s_addc_u32 s51, s7, 0
	global_load_dwordx4 v[32:35], v4, s[30:31]
	global_load_dwordx4 v[36:39], v4, s[30:31] offset:1024
	global_load_dwordx4 v[40:43], v4, s[30:31] offset:2048
	global_load_dwordx4 v[44:47], v4, s[30:31] offset:3072
	global_load_dwordx4 v[64:67], v4, s[36:37]
	global_load_dwordx4 v[68:71], v4, s[36:37] offset:1024
	global_load_dwordx4 v[72:75], v4, s[36:37] offset:2048
	global_load_dwordx4 v[76:79], v4, s[36:37] offset:3072
	global_load_dwordx4 v[80:83], v4, s[38:39]
	global_load_dwordx4 v[84:87], v4, s[38:39] offset:1024
	global_load_dwordx4 v[88:91], v4, s[38:39] offset:2048
	global_load_dwordx4 v[92:95], v4, s[38:39] offset:3072
	s_waitcnt vmcnt(16)
	v_mul_f32_e32 v7, v48, v48
	v_fmac_f32_e32 v7, v49, v49
	v_fmac_f32_e32 v7, v50, v50
	v_fmac_f32_e32 v7, v51, v51
	v_fmac_f32_e32 v7, v52, v52
	v_fmac_f32_e32 v7, v53, v53
	v_fmac_f32_e32 v7, v54, v54
	v_fmac_f32_e32 v7, v55, v55
	v_fmac_f32_e32 v7, v56, v56
	v_fmac_f32_e32 v7, v57, v57
	v_fmac_f32_e32 v7, v58, v58
	v_fmac_f32_e32 v7, v59, v59
	v_fmac_f32_e32 v7, v60, v60
	v_fmac_f32_e32 v7, v61, v61
	v_fmac_f32_e32 v7, v62, v62
	v_fmac_f32_e32 v7, v63, v63
	s_nop 1
	v_add_f32_dpp v7, v7, v7 quad_perm:[1,0,3,2] row_mask:0xf bank_mask:0xf
	s_nop 1
	v_add_f32_dpp v7, v7, v7 quad_perm:[2,3,0,1] row_mask:0xf bank_mask:0xf
	s_nop 1
	v_add_f32_dpp v7, v7, v7 row_half_mirror row_mask:0xf bank_mask:0xf
	s_nop 1
	v_add_f32_dpp v7, v7, v7 row_mirror row_mask:0xf bank_mask:0xf
	s_nop 1
	ds_bpermute_b32 v8, v5, v7
	s_waitcnt lgkmcnt(0)
	v_add_f32_e32 v7, v7, v8
	ds_bpermute_b32 v8, v6, v7
	s_waitcnt lgkmcnt(0)
	v_add_f32_e32 v7, v7, v8
	v_mov_b32_e32 v8, 0x358637bd
	v_fmac_f32_e32 v8, 0x3a800000, v7
	v_rsq_f32_e32 v8, v8
	s_nop 0
	v_mul_f32_e32 v48, v48, v8
	v_mul_f32_e32 v49, v49, v8
	v_mul_f32_e32 v50, v50, v8
	v_mul_f32_e32 v51, v51, v8
	v_mul_f32_e32 v52, v52, v8
	v_mul_f32_e32 v53, v53, v8
	v_mul_f32_e32 v54, v54, v8
	v_mul_f32_e32 v55, v55, v8
	v_mul_f32_e32 v56, v56, v8
	v_mul_f32_e32 v57, v57, v8
	v_mul_f32_e32 v58, v58, v8
	v_mul_f32_e32 v59, v59, v8
	v_mul_f32_e32 v60, v60, v8
	v_mul_f32_e32 v61, v61, v8
	v_mul_f32_e32 v62, v62, v8
	v_mul_f32_e32 v63, v63, v8
	v_mul_f32_e32 v48, v48, v16
	v_mul_f32_e32 v49, v49, v17
	v_mul_f32_e32 v50, v50, v18
	v_mul_f32_e32 v51, v51, v19
	v_mul_f32_e32 v52, v52, v20
	v_mul_f32_e32 v53, v53, v21
	v_mul_f32_e32 v54, v54, v22
	v_mul_f32_e32 v55, v55, v23
	v_mul_f32_e32 v56, v56, v24
	v_mul_f32_e32 v57, v57, v25
	v_mul_f32_e32 v58, v58, v26
	v_mul_f32_e32 v59, v59, v27
	v_mul_f32_e32 v60, v60, v28
	v_mul_f32_e32 v61, v61, v29
	v_mul_f32_e32 v62, v62, v30
	v_mul_f32_e32 v63, v63, v31
	v_add_f32_e32 v112, 1.0, v112
	v_add_f32_e32 v113, 1.0, v113
	v_add_f32_e32 v114, 1.0, v114
	v_add_f32_e32 v115, 1.0, v115
	v_add_f32_e32 v116, 1.0, v116
	v_add_f32_e32 v117, 1.0, v117
	v_add_f32_e32 v118, 1.0, v118
	v_add_f32_e32 v119, 1.0, v119
	v_add_f32_e32 v120, 1.0, v120
	v_add_f32_e32 v121, 1.0, v121
	v_add_f32_e32 v122, 1.0, v122
	v_add_f32_e32 v123, 1.0, v123
	v_add_f32_e32 v124, 1.0, v124
	v_add_f32_e32 v125, 1.0, v125
	v_add_f32_e32 v126, 1.0, v126
	v_add_f32_e32 v127, 1.0, v127
	v_fma_f32 v48, v48, v112, v96
	v_fma_f32 v49, v49, v113, v97
	v_fma_f32 v50, v50, v114, v98
	v_fma_f32 v51, v51, v115, v99
	v_fma_f32 v52, v52, v116, v100
	v_fma_f32 v53, v53, v117, v101
	v_fma_f32 v54, v54, v118, v102
	v_fma_f32 v55, v55, v119, v103
	v_fma_f32 v56, v56, v120, v104
	v_fma_f32 v57, v57, v121, v105
	v_fma_f32 v58, v58, v122, v106
	v_fma_f32 v59, v59, v123, v107
	v_fma_f32 v60, v60, v124, v108
	v_fma_f32 v61, v61, v125, v109
	v_fma_f32 v62, v62, v126, v110
	v_fma_f32 v63, v63, v127, v111
	v_cvt_pk_bf16_f32 v48, v48, v49
	v_cvt_pk_bf16_f32 v49, v50, v51
	v_cvt_pk_bf16_f32 v50, v52, v53
	v_cvt_pk_bf16_f32 v51, v54, v55
	v_cvt_pk_bf16_f32 v52, v56, v57
	v_cvt_pk_bf16_f32 v53, v58, v59
	v_cvt_pk_bf16_f32 v54, v60, v61
	v_cvt_pk_bf16_f32 v55, v62, v63
	s_nop 0
	global_store_dwordx2 v9, v[48:49], s[56:57]
	global_store_dwordx2 v9, v[50:51], s[56:57] offset:512
	global_store_dwordx2 v9, v[52:53], s[56:57] offset:1024
	global_store_dwordx2 v9, v[54:55], s[56:57] offset:1536
	s_cmp_lt_u32 s27, s26
	s_cbranch_scc1 .Ln1_top
	s_waitcnt vmcnt(0)
.Ln1_done:
.LBB0_362:
	s_or_b64 exec, exec, s[0:1]
	v_readlane_b32 s0, v254, 8
	s_waitcnt vmcnt(0)
	v_readlane_b32 s1, v254, 9
	s_xor_b64 s[62:63], s[0:1], -1
	s_barrier
	s_mov_b64 s[0:1], exec
	v_readlane_b32 s34, v253, 1
	v_readlane_b32 s35, v253, 2
	s_and_b64 s[34:35], s[0:1], s[34:35]
	s_mov_b64 exec, s[34:35]
	s_cbranch_execz .LBB0_414
	v_readlane_b32 s13, v255, 62
	s_waitcnt vmcnt(0) expcnt(0) lgkmcnt(0)
	s_nop 0
	v_mov_b32_e32 v0, s13
	ds_read_b32 v2, v0
	v_readlane_b32 s13, v255, 63
	s_waitcnt lgkmcnt(0)
	v_cmp_ne_u32_e32 vcc, 0, v2
	v_mov_b32_e32 v0, s13
	ds_read_b32 v0, v0
	s_cbranch_vccnz .LBB0_378
	s_mov_b32 s13, 1
	s_branch .LBB0_366

; DI int TID() { int t = threadIdx.x; asm volatile("" : "+v"(t)); return t; }
; DI void phase_norm(const Params& p, int l, int which, int bid, int nblk) {
;   const int lane = TID() & 63, w = TID() >> 6;
;   const float* g = (which ? p.in[I_G2] : p.in[I_G1]) + l * 1024;
;   const bool from_input = (which == 0 && l == 0);
;   for (int row = bid * 4 + w; row < ROWS; row += nblk * 4) {
;     const int b = row / TPB, pos = row % TPB;
;     if (which == 1 && l == 1 && pos < CTXL) continue;
;     const float* xr = xrow_ptr(p, from_input, b, pos);
;     const float* mod = WSP(const float, OFF_MOD) + (size_t)(l * 17 + (pos < CTXL ? 16 : b)) * 6144 + which * 3072;
.LBB0_1321:
	s_or_b64 exec, exec, s[34:35]
	s_waitcnt lgkmcnt(0)
	v_mov_b32_e32 v0, v218
	v_mov_b32_e32 v1, v218
	s_barrier
	s_mov_b64 s[34:35], exec
	v_readlane_b32 s18, v254, 10
	v_lshrrev_b32_e32 v4, 6, v218
	v_readlane_b32 s19, v255, 58
	v_and_b32_e32 v10, 63, v218
	v_readlane_b32 s48, v253, 17
	v_readlane_b32 s49, v253, 18
	v_readfirstlane_b32 s22, v4
	s_add_i32 s19, s19, s22
	s_mov_b32 s23, 99
	s_mov_b32 s25, 99
	s_movk_i32 s26, 18
	s_cmp_eq_u64 s[70:71], 0
	s_cbranch_scc1 .Ln2_noskip
	s_lshr_b32 s23, s19, 8
	s_add_i32 s25, s23, 9
	s_movk_i32 s26, 16
.Ln2_noskip:
	s_mul_i32 s65, s24, 17
	s_lshl_b32 s16, s24, 12
	s_add_u32 s48, s48, s16
	s_addc_u32 s49, s49, 0
	v_lshlrev_b32_e32 v4, 4, v10
	v_lshlrev_b32_e32 v9, 3, v10
	global_load_dwordx4 v[16:19], v4, s[48:49]
	global_load_dwordx4 v[20:23], v4, s[48:49] offset:1024
	global_load_dwordx4 v[24:27], v4, s[48:49] offset:2048
	global_load_dwordx4 v[28:31], v4, s[48:49] offset:3072
	v_xor_b32_e32 v5, 16, v10
	v_xor_b32_e32 v6, 32, v10
	v_lshlrev_b32_e32 v5, 2, v5
	v_lshlrev_b32_e32 v6, 2, v6
	s_mov_b32 s27, 0
	s_cmp_ge_u32 s27, s23
	s_addc_u32 s44, s27, 0
	s_cmp_ge_u32 s44, s25
	s_addc_u32 s44, s44, 0
	s_lshl_b32 s44, s44, 11
	s_add_i32 s44, s44, s19
	s_mul_hi_u32 s46, s44, 0x38e38e39
	s_lshr_b32 s46, s46, 9
	s_mul_i32 s16, s46, 0x900
	s_sub_u32 s16, s44, s16
	s_cmp_lt_u32 s16, 0x100
	s_cbranch_scc1 .Ln2_1_ctx
	s_lshl_b32 s17, s46, 11
	s_add_i32 s17, s17, s16
	s_add_i32 s17, s17, 0xffffff00
	s_lshl_b32 s17, s17, 12
	s_add_u32 s30, s94, s17
	s_addc_u32 s31, s95, 0
	s_add_i32 s46, s46, s65
	s_branch .Ln2_1_ptr
.Ln2_1_ctx:
	s_lshl_b32 s17, s46, 8
	s_add_i32 s17, s17, s16
	s_lshl_b32 s17, s17, 12
	s_add_u32 s30, s96, 0x17a00000
	s_addc_u32 s31, s97, 0
	s_add_u32 s30, s30, s17
	s_addc_u32 s31, s31, 0
	s_add_i32 s46, s65, 16
.Ln2_1_ptr:
	s_mul_i32 s46, s46, 0x6000
	s_add_u32 s36, s96, 0x1be07000
	s_addc_u32 s37, s97, 0
	s_add_u32 s36, s36, s46
	s_addc_u32 s37, s37, 0
	s_add_u32 s38, s36, 0x1000
	s_addc_u32 s39, s37, 0
	s_lshl_b32 s17, s44, 11
	s_add_u32 s50, s6, s17
	s_addc_u32 s51, s7, 0
	global_load_dwordx4 v[32:35], v4, s[30:31]
	global_load_dwordx4 v[36:39], v4, s[30:31] offset:1024
	global_load_dwordx4 v[40:43], v4, s[30:31] offset:2048
	global_load_dwordx4 v[44:47], v4, s[30:31] offset:3072
	global_load_dwordx4 v[64:67], v4, s[36:37]
	global_load_dwordx4 v[68:71], v4, s[36:37] offset:1024
	global_load_dwordx4 v[72:75], v4, s[36:37] offset:2048
	global_load_dwordx4 v[76:79], v4, s[36:37] offset:3072
	global_load_dwordx4 v[80:83], v4, s[38:39]
	global_load_dwordx4 v[84:87], v4, s[38:39] offset:1024
	global_load_dwordx4 v[88:91], v4, s[38:39] offset:2048
	global_load_dwordx4 v[92:95], v4, s[38:39] offset:3072
.Ln2_top:
	s_add_i32 s28, s27, 1
	s_cmp_ge_u32 s28, s23
	s_addc_u32 s44, s28, 0
	s_cmp_ge_u32 s44, s25
	s_addc_u32 s44, s44, 0
	s_lshl_b32 s44, s44, 11
	s_add_i32 s44, s44, s19
	s_mul_hi_u32 s46, s44, 0x38e38e39
	s_lshr_b32 s46, s46, 9
	s_mul_i32 s16, s46, 0x900
	s_sub_u32 s16, s44, s16
	s_cmp_lt_u32 s16, 0x100
	s_cbranch_scc1 .Ln2_2_ctx
	s_lshl_b32 s17, s46, 11
	s_add_i32 s17, s17, s16
	s_add_i32 s17, s17, 0xffffff00
	s_lshl_b32 s17, s17, 12
	s_add_u32 s30, s94, s17
	s_addc_u32 s31, s95, 0
	s_add_i32 s46, s46, s65
	s_branch .Ln2_2_ptr

; DI u32 pack2(float a, float b) { return (u32)f2bf(a) | ((u32)f2bf(b) << 16); }
; DI void phase_norm(const Params& p, int l, int which, int bid, int nblk) {
;     ...
;     float x[16];
; #pragma unroll
;     for (int hh = 0; hh < 2; ++hh) {
;       const float4 a = *(const float4*)(xr + hh * 512 + lane * 8);
;       const float4 c = *(const float4*)(xr + hh * 512 + lane * 8 + 4);
;       x[hh * 8 + 0] = a.x; x[hh * 8 + 1] = a.y; x[hh * 8 + 2] = a.z; x[hh * 8 + 3] = a.w;
;       x[hh * 8 + 4] = c.x; x[hh * 8 + 5] = c.y; x[hh * 8 + 6] = c.z; x[hh * 8 + 7] = c.w;
;     }
;     float ss = 0.f;
; #pragma unroll
;     for (int i = 0; i < 16; ++i) ss += x[i] * x[i];
;     ss = wave_sum(ss);
;     const float rs = rsqrtf(ss * (1.f / 1024.f) + EPSF);
; #pragma unroll
;     for (int hh = 0; hh < 2; ++hh) {
;       const int c0 = hh * 512 + lane * 8;
;       float y[8];
; #pragma unroll
;       for (int i = 0; i < 8; ++i) {
;         const float yn = x[hh * 8 + i] * rs * g[c0 + i];
;         y[i] = yn * (1.f + mod[1024 + c0 + i]) + mod[c0 + i];
;       }
;       uint4 o = {pack2(y[0], y[1]), pack2(y[2], y[3]), pack2(y[4], y[5]), pack2(y[6], y[7])};
;       *(uint4*)&WSP(u16, OFF_ACT)[(size_t)row * 1024 + c0] = o;
;     }
.Ln2_2_ptr:
	s_mul_i32 s46, s46, 0x6000
	s_add_u32 s36, s96, 0x1be07000
	s_addc_u32 s37, s97, 0
	s_add_u32 s36, s36, s46
	s_addc_u32 s37, s37, 0
	s_add_u32 s38, s36, 0x1000
	s_addc_u32 s39, s37, 0
	s_lshl_b32 s17, s44, 11
	s_add_u32 s56, s6, s17
	s_addc_u32 s57, s7, 0
	global_load_dwordx4 v[48:51], v4, s[30:31]
	global_load_dwordx4 v[52:55], v4, s[30:31] offset:1024
	global_load_dwordx4 v[56:59], v4, s[30:31] offset:2048
	global_load_dwordx4 v[60:63], v4, s[30:31] offset:3072
	global_load_dwordx4 v[96:99], v4, s[36:37]
	global_load_dwordx4 v[100:103], v4, s[36:37] offset:1024
	global_load_dwordx4 v[104:107], v4, s[36:37] offset:2048
	global_load_dwordx4 v[108:111], v4, s[36:37] offset:3072
	global_load_dwordx4 v[112:115], v4, s[38:39]
	global_load_dwordx4 v[116:119], v4, s[38:39] offset:1024
	global_load_dwordx4 v[120:123], v4, s[38:39] offset:2048
	global_load_dwordx4 v[124:127], v4, s[38:39] offset:3072
	s_waitcnt vmcnt(12)
	v_mul_f32_e32 v7, v32, v32
	v_fmac_f32_e32 v7, v33, v33
	v_fmac_f32_e32 v7, v34, v34
	v_fmac_f32_e32 v7, v35, v35
	v_fmac_f32_e32 v7, v36, v36
	v_fmac_f32_e32 v7, v37, v37
	v_fmac_f32_e32 v7, v38, v38
	v_fmac_f32_e32 v7, v39, v39
	v_fmac_f32_e32 v7, v40, v40
	v_fmac_f32_e32 v7, v41, v41
	v_fmac_f32_e32 v7, v42, v42
	v_fmac_f32_e32 v7, v43, v43
	v_fmac_f32_e32 v7, v44, v44
	v_fmac_f32_e32 v7, v45, v45
	v_fmac_f32_e32 v7, v46, v46
	v_fmac_f32_e32 v7, v47, v47
	s_nop 1
	v_add_f32_dpp v7, v7, v7 quad_perm:[1,0,3,2] row_mask:0xf bank_mask:0xf
	s_nop 1
	v_add_f32_dpp v7, v7, v7 quad_perm:[2,3,0,1] row_mask:0xf bank_mask:0xf
	s_nop 1
	v_add_f32_dpp v7, v7, v7 row_half_mirror row_mask:0xf bank_mask:0xf
	s_nop 1
	v_add_f32_dpp v7, v7, v7 row_mirror row_mask:0xf bank_mask:0xf
	s_nop 1
	ds_bpermute_b32 v8, v5, v7
	s_waitcnt lgkmcnt(0)
	v_add_f32_e32 v7, v7, v8
	ds_bpermute_b32 v8, v6, v7
	s_waitcnt lgkmcnt(0)
	v_add_f32_e32 v7, v7, v8
	v_mov_b32_e32 v8, 0x358637bd
	v_fmac_f32_e32 v8, 0x3a800000, v7
	v_rsq_f32_e32 v8, v8
	s_nop 0
	v_mul_f32_e32 v32, v32, v8
	v_mul_f32_e32 v33, v33, v8
	v_mul_f32_e32 v34, v34, v8
	v_mul_f32_e32 v35, v35, v8
	v_mul_f32_e32 v36, v36, v8
	v_mul_f32_e32 v37, v37, v8
	v_mul_f32_e32 v38, v38, v8
	v_mul_f32_e32 v39, v39, v8
	v_mul_f32_e32 v40, v40, v8
	v_mul_f32_e32 v41, v41, v8
	v_mul_f32_e32 v42, v42, v8
	v_mul_f32_e32 v43, v43, v8
	v_mul_f32_e32 v44, v44, v8
	v_mul_f32_e32 v45, v45, v8
	v_mul_f32_e32 v46, v46, v8
	v_mul_f32_e32 v47, v47, v8
	v_mul_f32_e32 v32, v32, v16
	v_mul_f32_e32 v33, v33, v17
	v_mul_f32_e32 v34, v34, v18
	v_mul_f32_e32 v35, v35, v19
	v_mul_f32_e32 v36, v36, v20
	v_mul_f32_e32 v37, v37, v21
	v_mul_f32_e32 v38, v38, v22
	v_mul_f32_e32 v39, v39, v23
	v_mul_f32_e32 v40, v40, v24
	v_mul_f32_e32 v41, v41, v25
	v_mul_f32_e32 v42, v42, v26
	v_mul_f32_e32 v43, v43, v27
	v_mul_f32_e32 v44, v44, v28
	v_mul_f32_e32 v45, v45, v29
	v_mul_f32_e32 v46, v46, v30
	v_mul_f32_e32 v47, v47, v31
	v_add_f32_e32 v80, 1.0, v80
	v_add_f32_e32 v81, 1.0, v81
	v_add_f32_e32 v82, 1.0, v82
	v_add_f32_e32 v83, 1.0, v83
	v_add_f32_e32 v84, 1.0, v84
	v_add_f32_e32 v85, 1.0, v85
	v_add_f32_e32 v86, 1.0, v86
	v_add_f32_e32 v87, 1.0, v87
	v_add_f32_e32 v88, 1.0, v88
	v_add_f32_e32 v89, 1.0, v89
	v_add_f32_e32 v90, 1.0, v90
	v_add_f32_e32 v91, 1.0, v91
	v_add_f32_e32 v92, 1.0, v92
	v_add_f32_e32 v93, 1.0, v93
	v_add_f32_e32 v94, 1.0, v94
	v_add_f32_e32 v95, 1.0, v95
	v_fma_f32 v32, v32, v80, v64
	v_fma_f32 v33, v33, v81, v65
	v_fma_f32 v34, v34, v82, v66
	v_fma_f32 v35, v35, v83, v67
	v_fma_f32 v36, v36, v84, v68
	v_fma_f32 v37, v37, v85, v69
	v_fma_f32 v38, v38, v86, v70
	v_fma_f32 v39, v39, v87, v71
	v_fma_f32 v40, v40, v88, v72
	v_fma_f32 v41, v41, v89, v73
	v_fma_f32 v42, v42, v90, v74
	v_fma_f32 v43, v43, v91, v75
	v_fma_f32 v44, v44, v92, v76
	v_fma_f32 v45, v45, v93, v77
	v_fma_f32 v46, v46, v94, v78
	v_fma_f32 v47, v47, v95, v79
	v_cvt_pk_bf16_f32 v32, v32, v33
	v_cvt_pk_bf16_f32 v33, v34, v35
	v_cvt_pk_bf16_f32 v34, v36, v37
	v_cvt_pk_bf16_f32 v35, v38, v39
	v_cvt_pk_bf16_f32 v36, v40, v41
	v_cvt_pk_bf16_f32 v37, v42, v43
	v_cvt_pk_bf16_f32 v38, v44, v45
	v_cvt_pk_bf16_f32 v39, v46, v47
	s_nop 0
	global_store_dwordx2 v9, v[32:33], s[50:51]
	global_store_dwordx2 v9, v[34:35], s[50:51] offset:512
	global_store_dwordx2 v9, v[36:37], s[50:51] offset:1024
	global_store_dwordx2 v9, v[38:39], s[50:51] offset:1536
	s_add_i32 s27, s27, 2
	s_cmp_lt_u32 s27, s26
	s_cselect_b32 s28, s27, 0
	s_cmp_ge_u32 s28, s23
	s_addc_u32 s44, s28, 0
	s_cmp_ge_u32 s44, s25
	s_addc_u32 s44, s44, 0
	s_lshl_b32 s44, s44, 11
	s_add_i32 s44, s44, s19
	s_mul_hi_u32 s46, s44, 0x38e38e39
	s_lshr_b32 s46, s46, 9
	s_mul_i32 s16, s46, 0x900
	s_sub_u32 s16, s44, s16
	s_cmp_lt_u32 s16, 0x100
	s_cbranch_scc1 .Ln2_3_ctx
	s_lshl_b32 s17, s46, 11
	s_add_i32 s17, s17, s16
	s_add_i32 s17, s17, 0xffffff00
	s_lshl_b32 s17, s17, 12
	s_add_u32 s30, s94, s17
	s_addc_u32 s31, s95, 0
	s_add_i32 s46, s46, s65
	s_branch .Ln2_3_ptr

; DI u32 pack2(float a, float b) { return (u32)f2bf(a) | ((u32)f2bf(b) << 16); }
; DI void phase_norm(const Params& p, int l, int which, int bid, int nblk) {
;     ...
;     float x[16];
; #pragma unroll
;     for (int hh = 0; hh < 2; ++hh) {
;       const float4 a = *(const float4*)(xr + hh * 512 + lane * 8);
;       const float4 c = *(const float4*)(xr + hh * 512 + lane * 8 + 4);
;       x[hh * 8 + 0] = a.x; x[hh * 8 + 1] = a.y; x[hh * 8 + 2] = a.z; x[hh * 8 + 3] = a.w;
;       x[hh * 8 + 4] = c.x; x[hh * 8 + 5] = c.y; x[hh * 8 + 6] = c.z; x[hh * 8 + 7] = c.w;
;     }
;     float ss = 0.f;
; #pragma unroll
;     for (int i = 0; i < 16; ++i) ss += x[i] * x[i];
;     ss = wave_sum(ss);
;     const float rs = rsqrtf(ss * (1.f / 1024.f) + EPSF);
; #pragma unroll
;     for (int hh = 0; hh < 2; ++hh) {
;       const int c0 = hh * 512 + lane * 8;
;       float y[8];
; #pragma unroll
;       for (int i = 0; i < 8; ++i) {
;         const float yn = x[hh * 8 + i] * rs * g[c0 + i];
;         y[i] = yn * (1.f + mod[1024 + c0 + i]) + mod[c0 + i];
;       }
;       uint4 o = {pack2(y[0], y[1]), pack2(y[2], y[3]), pack2(y[4], y[5]), pack2(y[6], y[7])};
;       *(uint4*)&WSP(u16, OFF_ACT)[(size_t)row * 1024 + c0] = o;
;     }
.Ln2_3_ptr:
	s_mul_i32 s46, s46, 0x6000
	s_add_u32 s36, s96, 0x1be07000
	s_addc_u32 s37, s97, 0
	s_add_u32 s36, s36, s46
	s_addc_u32 s37, s37, 0
	s_add_u32 s38, s36, 0x1000
	s_addc_u32 s39, s37, 0
	s_lshl_b32 s17, s44, 11
	s_add_u32 s50, s6, s17
	s_addc_u32 s51, s7, 0
	global_load_dwordx4 v[32:35], v4, s[30:31]
	global_load_dwordx4 v[36:39], v4, s[30:31] offset:1024
	global_load_dwordx4 v[40:43], v4, s[30:31] offset:2048
	global_load_dwordx4 v[44:47], v4, s[30:31] offset:3072
	global_load_dwordx4 v[64:67], v4, s[36:37]
	global_load_dwordx4 v[68:71], v4, s[36:37] offset:1024
	global_load_dwordx4 v[72:75], v4, s[36:37] offset:2048
	global_load_dwordx4 v[76:79], v4, s[36:37] offset:3072
	global_load_dwordx4 v[80:83], v4, s[38:39]
	global_load_dwordx4 v[84:87], v4, s[38:39] offset:1024
	global_load_dwordx4 v[88:91], v4, s[38:39] offset:2048
	global_load_dwordx4 v[92:95], v4, s[38:39] offset:3072
	s_waitcnt vmcnt(16)
	v_mul_f32_e32 v7, v48, v48
	v_fmac_f32_e32 v7, v49, v49
	v_fmac_f32_e32 v7, v50, v50
	v_fmac_f32_e32 v7, v51, v51
	v_fmac_f32_e32 v7, v52, v52
	v_fmac_f32_e32 v7, v53, v53
	v_fmac_f32_e32 v7, v54, v54
	v_fmac_f32_e32 v7, v55, v55
	v_fmac_f32_e32 v7, v56, v56
	v_fmac_f32_e32 v7, v57, v57
	v_fmac_f32_e32 v7, v58, v58
	v_fmac_f32_e32 v7, v59, v59
	v_fmac_f32_e32 v7, v60, v60
	v_fmac_f32_e32 v7, v61, v61
	v_fmac_f32_e32 v7, v62, v62
	v_fmac_f32_e32 v7, v63, v63
	s_nop 1
	v_add_f32_dpp v7, v7, v7 quad_perm:[1,0,3,2] row_mask:0xf bank_mask:0xf
	s_nop 1
	v_add_f32_dpp v7, v7, v7 quad_perm:[2,3,0,1] row_mask:0xf bank_mask:0xf
	s_nop 1
	v_add_f32_dpp v7, v7, v7 row_half_mirror row_mask:0xf bank_mask:0xf
	s_nop 1
	v_add_f32_dpp v7, v7, v7 row_mirror row_mask:0xf bank_mask:0xf
	s_nop 1
	ds_bpermute_b32 v8, v5, v7
	s_waitcnt lgkmcnt(0)
	v_add_f32_e32 v7, v7, v8
	ds_bpermute_b32 v8, v6, v7
	s_waitcnt lgkmcnt(0)
	v_add_f32_e32 v7, v7, v8
	v_mov_b32_e32 v8, 0x358637bd
	v_fmac_f32_e32 v8, 0x3a800000, v7
	v_rsq_f32_e32 v8, v8
	s_nop 0
	v_mul_f32_e32 v48, v48, v8
	v_mul_f32_e32 v49, v49, v8
	v_mul_f32_e32 v50, v50, v8
	v_mul_f32_e32 v51, v51, v8
	v_mul_f32_e32 v52, v52, v8
	v_mul_f32_e32 v53, v53, v8
	v_mul_f32_e32 v54, v54, v8
	v_mul_f32_e32 v55, v55, v8
	v_mul_f32_e32 v56, v56, v8
	v_mul_f32_e32 v57, v57, v8
	v_mul_f32_e32 v58, v58, v8
	v_mul_f32_e32 v59, v59, v8
	v_mul_f32_e32 v60, v60, v8
	v_mul_f32_e32 v61, v61, v8
	v_mul_f32_e32 v62, v62, v8
	v_mul_f32_e32 v63, v63, v8
	v_mul_f32_e32 v48, v48, v16
	v_mul_f32_e32 v49, v49, v17
	v_mul_f32_e32 v50, v50, v18
	v_mul_f32_e32 v51, v51, v19
	v_mul_f32_e32 v52, v52, v20
	v_mul_f32_e32 v53, v53, v21
	v_mul_f32_e32 v54, v54, v22
	v_mul_f32_e32 v55, v55, v23
	v_mul_f32_e32 v56, v56, v24
	v_mul_f32_e32 v57, v57, v25
	v_mul_f32_e32 v58, v58, v26
	v_mul_f32_e32 v59, v59, v27
	v_mul_f32_e32 v60, v60, v28
	v_mul_f32_e32 v61, v61, v29
	v_mul_f32_e32 v62, v62, v30
	v_mul_f32_e32 v63, v63, v31
	v_add_f32_e32 v112, 1.0, v112
	v_add_f32_e32 v113, 1.0, v113
	v_add_f32_e32 v114, 1.0, v114
	v_add_f32_e32 v115, 1.0, v115
	v_add_f32_e32 v116, 1.0, v116
	v_add_f32_e32 v117, 1.0, v117
	v_add_f32_e32 v118, 1.0, v118
	v_add_f32_e32 v119, 1.0, v119
	v_add_f32_e32 v120, 1.0, v120
	v_add_f32_e32 v121, 1.0, v121
	v_add_f32_e32 v122, 1.0, v122
	v_add_f32_e32 v123, 1.0, v123
	v_add_f32_e32 v124, 1.0, v124
	v_add_f32_e32 v125, 1.0, v125
	v_add_f32_e32 v126, 1.0, v126
	v_add_f32_e32 v127, 1.0, v127
	v_fma_f32 v48, v48, v112, v96
	v_fma_f32 v49, v49, v113, v97
	v_fma_f32 v50, v50, v114, v98
	v_fma_f32 v51, v51, v115, v99
	v_fma_f32 v52, v52, v116, v100
	v_fma_f32 v53, v53, v117, v101
	v_fma_f32 v54, v54, v118, v102
	v_fma_f32 v55, v55, v119, v103
	v_fma_f32 v56, v56, v120, v104
	v_fma_f32 v57, v57, v121, v105
	v_fma_f32 v58, v58, v122, v106
	v_fma_f32 v59, v59, v123, v107
	v_fma_f32 v60, v60, v124, v108
	v_fma_f32 v61, v61, v125, v109
	v_fma_f32 v62, v62, v126, v110
	v_fma_f32 v63, v63, v127, v111
	v_cvt_pk_bf16_f32 v48, v48, v49
	v_cvt_pk_bf16_f32 v49, v50, v51
	v_cvt_pk_bf16_f32 v50, v52, v53
	v_cvt_pk_bf16_f32 v51, v54, v55
	v_cvt_pk_bf16_f32 v52, v56, v57
	v_cvt_pk_bf16_f32 v53, v58, v59
	v_cvt_pk_bf16_f32 v54, v60, v61
	v_cvt_pk_bf16_f32 v55, v62, v63
	s_nop 0
	global_store_dwordx2 v9, v[48:49], s[56:57]
	global_store_dwordx2 v9, v[50:51], s[56:57] offset:512
	global_store_dwordx2 v9, v[52:53], s[56:57] offset:1024
	global_store_dwordx2 v9, v[54:55], s[56:57] offset:1536
	s_cmp_lt_u32 s27, s26
	s_cbranch_scc1 .Ln2_top
	s_waitcnt vmcnt(0)
